# v24 + hand-written store-only epilogues for in-proj / uq / ukv (kinds 0,1,2): tile-uniform region select, SGPR base + precomputed 32-bit offsets, no per-combo dispatch
# speedup vs baseline: 1.0203x; 1.0075x over previous
; #define PG8_STAGE(bufoff, gbase, voff) do { _Pragma("unroll") for (int _i = 0; _i < 2; ++_i) \
;     __builtin_amdgcn_global_load_lds((const unsigned*)((const char*)(gbase) + (voff)[_i]), (LAS unsigned*)(lds + (bufoff) + ldsw + _i * 8192), 16, 0, 0); } while (0)
; #define PG8_LDA(dst, b, h) do { _Pragma("unroll") for (int m = 0; m < 4; ++m) _Pragma("unroll") for (int k = 0; k < 2; ++k) dst[m][k] = *(const LAS bf16x8*)(lds + PG8_SA(b, h) + aoff + m * 2048 + k * 1024); } while (0)
; #define PG8_LDB(dst, b, h) do { _Pragma("unroll") for (int n = 0; n < 2; ++n) _Pragma("unroll") for (int k = 0; k < 2; ++k) dst[n][k] = *(const LAS bf16x8*)(lds + PG8_SB(b, h) + boff + n * 2048 + k * 1024); } while (0)
; #define PG8_MMA(ai, bj, At, Bt) do { __builtin_amdgcn_s_setprio(1); _Pragma("unroll") for (int m = 0; m < 4; ++m) _Pragma("unroll") for (int n = 0; n < 2; ++n) _Pragma("unroll") for (int k = 0; k < 2; ++k) \
;     acc[ai][bj][m][n] = __builtin_amdgcn_mfma_f32_16x16x32_bf16(Bt[n][k], At[m][k], acc[ai][bj][m][n], 0, 0, 0); __builtin_amdgcn_s_setprio(0); } while (0)
; #define PG8_WAIT_L(n) asm volatile("s_waitcnt lgkmcnt(" #n ")" ::: "memory")
; #define PG8_BAR __builtin_amdgcn_s_barrier()
; #define PG8_SCHED __builtin_amdgcn_sched_barrier(0)
; template <class Epi>
; __device__ __forceinline__ void gemm_phase(LAS unsigned char* lds, const Gemm g, const Epi& E) {
;     ...
;     for (int t = 0; t < nt; t += 2) {
;       const bool last = (t == nt - 2);
;       const char* a1 = cA + (size_t)(t + 1) * kstep;
;       const char* a2 = last ? nA : cA + (size_t)(t + 2) * kstep; const char* b2 = last ? nB : cB + (size_t)(t + 2) * kstep;
;       const char* a3 = a2 + kstep; const char* b3 = b2 + kstep;
;       PG8_LDB(B0, 0, 0); PG8_SCHED; PG8_LDA(At, 0, 0); PG8_STAGE(PG8_SA(1, 1), a1 + hstepA, voffA);
;       PG8_WAIT_L(8); PG8_BAR; PG8_WAIT_L(0); PG8_MMA(0, 0, At, B0); PG8_BAR; PG8_SCHED;
;       PG8_LDB(B1, 0, 1); PG8_STAGE(PG8_SB(0, 0), b2, voffB);
;       PG8_BAR; PG8_WAIT_L(0); PG8_MMA(0, 1, At, B1); PG8_BAR;
;       PG8_LDA(At, 0, 1); PG8_STAGE(PG8_SA(0, 0), a2, voffA);
;       PG8_BAR; PG8_WAIT_L(0); PG8_MMA(1, 0, At, B0); PG8_BAR; PG8_SCHED;
.LBB0_579:
	s_add_i32 s76, s26, 2
	s_add_u32 s28, s2, 0x80
	s_addc_u32 s27, s3, 0
	s_add_i32 s83, 0, 0x10000
	v_add_u32_e32 v156, s83, v173
	ds_read_b128 v[128:131], v156
	ds_read_b128 v[148:151], v156 offset:1024
	ds_read_b128 v[152:155], v156 offset:2048
	ds_read_b128 v[156:159], v156 offset:3072
	s_cmp_eq_u32 s89, s26
	s_cselect_b32 s26, s0, s28
	s_cselect_b32 s27, s1, s27
	s_cselect_b32 s29, s21, s39
	s_cselect_b32 s28, s20, s38
	v_lshl_add_u64 v[196:197], s[2:3], 0, v[144:145]
	s_add_i32 m0, s84, 0xc000
	ds_read_b128 v[160:163], v175
	ds_read_b128 v[164:167], v175 offset:1024
	ds_read_b128 v[168:171], v175 offset:2048
	ds_read_b128 v[176:179], v175 offset:3072
	ds_read_b128 v[180:183], v175 offset:4096
	ds_read_b128 v[184:187], v175 offset:5120
	ds_read_b128 v[188:191], v175 offset:6144
	ds_read_b128 v[192:195], v175 offset:7168
	global_load_lds_dwordx4 v[196:197], off
	v_lshl_add_u64 v[196:197], s[2:3], 0, v[146:147]
	s_add_i32 m0, s84, 0xe000
	s_nop 0
	global_load_lds_dwordx4 v[196:197], off
	s_waitcnt lgkmcnt(8)
	s_barrier
	s_waitcnt lgkmcnt(0)
	s_setprio 1
	s_waitcnt lgkmcnt(0)
	v_mfma_f32_16x16x32_bf16 v[124:127], v[128:131], v[160:163], v[124:127]
	v_mfma_f32_16x16x32_bf16 v[120:123], v[152:155], v[160:163], v[120:123]
	v_mfma_f32_16x16x32_bf16 v[108:111], v[128:131], v[168:171], v[108:111]
	v_mfma_f32_16x16x32_bf16 v[104:107], v[152:155], v[168:171], v[104:107]
	v_mfma_f32_16x16x32_bf16 v[92:95], v[128:131], v[180:183], v[92:95]
	v_mfma_f32_16x16x32_bf16 v[88:91], v[152:155], v[180:183], v[88:91]
	v_mfma_f32_16x16x32_bf16 v[76:79], v[128:131], v[188:191], v[76:79]
	v_mfma_f32_16x16x32_bf16 v[72:75], v[152:155], v[188:191], v[72:75]
	v_mfma_f32_16x16x32_bf16 v[124:127], v[148:151], v[164:167], v[124:127]
	v_mfma_f32_16x16x32_bf16 v[120:123], v[156:159], v[164:167], v[120:123]
	v_mfma_f32_16x16x32_bf16 v[108:111], v[148:151], v[176:179], v[108:111]
	v_mfma_f32_16x16x32_bf16 v[104:107], v[156:159], v[176:179], v[104:107]
	v_mfma_f32_16x16x32_bf16 v[92:95], v[148:151], v[184:187], v[92:95]
	v_mfma_f32_16x16x32_bf16 v[88:91], v[156:159], v[184:187], v[88:91]
	v_mfma_f32_16x16x32_bf16 v[76:79], v[148:151], v[192:195], v[76:79]
	v_mfma_f32_16x16x32_bf16 v[72:75], v[156:159], v[192:195], v[72:75]
	s_setprio 0
	s_barrier
	s_add_i32 s94, 0, 0x14000
	s_add_i32 s83, s83, s97
	v_add_u32_e32 v208, s94, v173
	v_lshl_add_u64 v[212:213], s[28:29], 0, v[132:133]
	s_mov_b32 m0, s83
	ds_read_b128 v[196:199], v208
	ds_read_b128 v[200:203], v208 offset:1024
	ds_read_b128 v[204:207], v208 offset:2048
	ds_read_b128 v[208:211], v208 offset:3072
	global_load_lds_dwordx4 v[212:213], off
	v_lshl_add_u64 v[214:215], s[28:29], 0, v[142:143]
	s_add_i32 m0, s83, 0x2000
	s_nop 0
	global_load_lds_dwordx4 v[214:215], off
	s_barrier
	s_waitcnt lgkmcnt(0)
	s_setprio 1
	s_waitcnt lgkmcnt(0)
	v_mfma_f32_16x16x32_bf16 v[116:119], v[196:199], v[160:163], v[116:119]
	v_mfma_f32_16x16x32_bf16 v[112:115], v[204:207], v[160:163], v[112:115]
	v_mfma_f32_16x16x32_bf16 v[100:103], v[196:199], v[168:171], v[100:103]
	v_mfma_f32_16x16x32_bf16 v[96:99], v[204:207], v[168:171], v[96:99]
	v_mfma_f32_16x16x32_bf16 v[84:87], v[196:199], v[180:183], v[84:87]
	v_mfma_f32_16x16x32_bf16 v[80:83], v[204:207], v[180:183], v[80:83]
	v_mfma_f32_16x16x32_bf16 v[68:71], v[196:199], v[188:191], v[68:71]
	v_mfma_f32_16x16x32_bf16 v[64:67], v[204:207], v[188:191], v[64:67]
	v_mfma_f32_16x16x32_bf16 v[116:119], v[200:203], v[164:167], v[116:119]
	v_mfma_f32_16x16x32_bf16 v[112:115], v[208:211], v[164:167], v[112:115]
	v_mfma_f32_16x16x32_bf16 v[100:103], v[200:203], v[176:179], v[100:103]
	v_mfma_f32_16x16x32_bf16 v[96:99], v[208:211], v[176:179], v[96:99]
	v_mfma_f32_16x16x32_bf16 v[84:87], v[200:203], v[184:187], v[84:87]
	v_mfma_f32_16x16x32_bf16 v[80:83], v[208:211], v[184:187], v[80:83]
	v_mfma_f32_16x16x32_bf16 v[68:71], v[200:203], v[192:195], v[68:71]
	v_mfma_f32_16x16x32_bf16 v[64:67], v[208:211], v[192:195], v[64:67]
	s_setprio 0
	s_mov_b32 m0, s84
	v_lshl_add_u64 v[216:217], s[26:27], 0, v[138:139]
	s_barrier
	ds_read_b128 v[160:163], v175 offset:16384
	ds_read_b128 v[164:167], v175 offset:17408
	ds_read_b128 v[168:171], v175 offset:18432
	ds_read_b128 v[176:179], v175 offset:19456
	ds_read_b128 v[180:183], v175 offset:20480
	ds_read_b128 v[184:187], v175 offset:21504
	ds_read_b128 v[188:191], v175 offset:22528
	ds_read_b128 v[192:195], v175 offset:23552
	global_load_lds_dwordx4 v[216:217], off
	v_lshl_add_u64 v[218:219], s[26:27], 0, v[140:141]
	s_mov_b32 m0, s85
	s_nop 0
	global_load_lds_dwordx4 v[218:219], off
	s_barrier
	s_waitcnt lgkmcnt(0)
	s_setprio 1
	s_waitcnt lgkmcnt(0)
	v_mfma_f32_16x16x32_bf16 v[60:63], v[128:131], v[160:163], v[60:63]
	v_mfma_f32_16x16x32_bf16 v[56:59], v[152:155], v[160:163], v[56:59]
	v_mfma_f32_16x16x32_bf16 v[44:47], v[128:131], v[168:171], v[44:47]
	v_mfma_f32_16x16x32_bf16 v[40:43], v[152:155], v[168:171], v[40:43]
	v_mfma_f32_16x16x32_bf16 v[28:31], v[128:131], v[180:183], v[28:31]
	v_mfma_f32_16x16x32_bf16 v[24:27], v[152:155], v[180:183], v[24:27]
	v_mfma_f32_16x16x32_bf16 v[12:15], v[128:131], v[188:191], v[12:15]
	v_mfma_f32_16x16x32_bf16 v[8:11], v[152:155], v[188:191], v[8:11]
	v_mfma_f32_16x16x32_bf16 v[60:63], v[148:151], v[164:167], v[60:63]
	v_mfma_f32_16x16x32_bf16 v[56:59], v[156:159], v[164:167], v[56:59]
	v_mfma_f32_16x16x32_bf16 v[44:47], v[148:151], v[176:179], v[44:47]
	v_mfma_f32_16x16x32_bf16 v[40:43], v[156:159], v[176:179], v[40:43]
	v_mfma_f32_16x16x32_bf16 v[28:31], v[148:151], v[184:187], v[28:31]
	v_mfma_f32_16x16x32_bf16 v[24:27], v[156:159], v[184:187], v[24:27]
	v_mfma_f32_16x16x32_bf16 v[12:15], v[148:151], v[192:195], v[12:15]
	v_mfma_f32_16x16x32_bf16 v[8:11], v[156:159], v[192:195], v[8:11]
	s_setprio 0
	s_barrier
; #define PG8_STAGE(bufoff, gbase, voff) do { _Pragma("unroll") for (int _i = 0; _i < 2; ++_i) \
;     __builtin_amdgcn_global_load_lds((const unsigned*)((const char*)(gbase) + (voff)[_i]), (LAS unsigned*)(lds + (bufoff) + ldsw + _i * 8192), 16, 0, 0); } while (0)
; #define PG8_LDA(dst, b, h) do { _Pragma("unroll") for (int m = 0; m < 4; ++m) _Pragma("unroll") for (int k = 0; k < 2; ++k) dst[m][k] = *(const LAS bf16x8*)(lds + PG8_SA(b, h) + aoff + m * 2048 + k * 1024); } while (0)
; #define PG8_LDB(dst, b, h) do { _Pragma("unroll") for (int n = 0; n < 2; ++n) _Pragma("unroll") for (int k = 0; k < 2; ++k) dst[n][k] = *(const LAS bf16x8*)(lds + PG8_SB(b, h) + boff + n * 2048 + k * 1024); } while (0)
; #define PG8_MMA(ai, bj, At, Bt) do { __builtin_amdgcn_s_setprio(1); _Pragma("unroll") for (int m = 0; m < 4; ++m) _Pragma("unroll") for (int n = 0; n < 2; ++n) _Pragma("unroll") for (int k = 0; k < 2; ++k) \
;     acc[ai][bj][m][n] = __builtin_amdgcn_mfma_f32_16x16x32_bf16(Bt[n][k], At[m][k], acc[ai][bj][m][n], 0, 0, 0); __builtin_amdgcn_s_setprio(0); } while (0)
; #define PG8_WAIT_V(n) asm volatile("s_waitcnt vmcnt(" #n ")" ::: "memory")
; #define PG8_WAIT_L(n) asm volatile("s_waitcnt lgkmcnt(" #n ")" ::: "memory")
; #define PG8_BAR __builtin_amdgcn_s_barrier()
; #define PG8_SCHED __builtin_amdgcn_sched_barrier(0)
; template <class Epi>
; __device__ __forceinline__ void gemm_phase(LAS unsigned char* lds, const Gemm g, const Epi& E) {
;     ...
;       PG8_STAGE(PG8_SB(0, 1), b2 + hstepB, voffB);
;       PG8_WAIT_V(6); PG8_BAR; PG8_MMA(1, 1, At, B1); PG8_BAR;
;       PG8_LDB(B0, 1, 0); PG8_SCHED; PG8_LDA(At, 1, 0); PG8_STAGE(PG8_SA(0, 1), a2 + hstepA, voffA);
;       PG8_WAIT_L(8); PG8_BAR; PG8_WAIT_L(0); PG8_MMA(0, 0, At, B0); PG8_BAR; PG8_SCHED;
;       PG8_LDB(B1, 1, 1); PG8_STAGE(PG8_SB(1, 0), b3, voffB);
;       PG8_BAR; PG8_WAIT_L(0); PG8_MMA(0, 1, At, B1); PG8_BAR;
	s_add_u32 s28, s28, s95
	s_addc_u32 s29, s29, 0
	s_add_i32 s83, s94, s97
	v_lshl_add_u64 v[220:221], s[28:29], 0, v[132:133]
	s_mov_b32 m0, s83
	v_lshl_add_u64 v[222:223], s[28:29], 0, v[142:143]
	global_load_lds_dwordx4 v[220:221], off
	s_add_i32 m0, s83, 0x2000
	s_nop 0
	global_load_lds_dwordx4 v[222:223], off
	s_waitcnt vmcnt(6)
	s_barrier
	s_setprio 1
	v_mfma_f32_16x16x32_bf16 v[52:55], v[196:199], v[160:163], v[52:55]
	v_mfma_f32_16x16x32_bf16 v[48:51], v[204:207], v[160:163], v[48:51]
	v_mfma_f32_16x16x32_bf16 v[36:39], v[196:199], v[168:171], v[36:39]
	v_mfma_f32_16x16x32_bf16 v[32:35], v[204:207], v[168:171], v[32:35]
	v_mfma_f32_16x16x32_bf16 v[20:23], v[196:199], v[180:183], v[20:23]
	v_mfma_f32_16x16x32_bf16 v[16:19], v[204:207], v[180:183], v[16:19]
	v_mfma_f32_16x16x32_bf16 v[4:7], v[196:199], v[188:191], v[4:7]
	v_mfma_f32_16x16x32_bf16 v[0:3], v[204:207], v[188:191], v[0:3]
	v_mfma_f32_16x16x32_bf16 v[52:55], v[200:203], v[164:167], v[52:55]
	v_mfma_f32_16x16x32_bf16 v[48:51], v[208:211], v[164:167], v[48:51]
	v_mfma_f32_16x16x32_bf16 v[36:39], v[200:203], v[176:179], v[36:39]
	v_mfma_f32_16x16x32_bf16 v[32:35], v[208:211], v[176:179], v[32:35]
	v_mfma_f32_16x16x32_bf16 v[20:23], v[200:203], v[184:187], v[20:23]
	v_mfma_f32_16x16x32_bf16 v[16:19], v[208:211], v[184:187], v[16:19]
	v_mfma_f32_16x16x32_bf16 v[4:7], v[200:203], v[192:195], v[4:7]
	v_mfma_f32_16x16x32_bf16 v[0:3], v[208:211], v[192:195], v[0:3]
	s_setprio 0
	s_add_i32 s28, 0, 0x18000
	v_add_u32_e32 v156, s28, v173
	s_barrier
	ds_read_b128 v[128:131], v156
	ds_read_b128 v[148:151], v156 offset:1024
	ds_read_b128 v[152:155], v156 offset:2048
	ds_read_b128 v[156:159], v156 offset:3072
	s_add_u32 s26, s26, s56
	s_addc_u32 s27, s27, 0
	s_mov_b32 m0, s86
	v_lshl_add_u64 v[196:197], s[26:27], 0, v[138:139]
	ds_read_b128 v[160:163], v175 offset:32768
	ds_read_b128 v[164:167], v175 offset:33792
	ds_read_b128 v[168:171], v175 offset:34816
	ds_read_b128 v[176:179], v175 offset:35840
	ds_read_b128 v[180:183], v175 offset:36864
	ds_read_b128 v[184:187], v175 offset:37888
	ds_read_b128 v[188:191], v175 offset:38912
	ds_read_b128 v[192:195], v175 offset:39936
	global_load_lds_dwordx4 v[196:197], off
	v_lshl_add_u64 v[196:197], s[26:27], 0, v[140:141]
	s_mov_b32 m0, s87
	s_nop 0
	global_load_lds_dwordx4 v[196:197], off
	s_waitcnt lgkmcnt(8)
	s_barrier
	s_waitcnt lgkmcnt(0)
	s_setprio 1
	s_waitcnt lgkmcnt(0)
	v_mfma_f32_16x16x32_bf16 v[124:127], v[128:131], v[160:163], v[124:127]
	v_mfma_f32_16x16x32_bf16 v[120:123], v[152:155], v[160:163], v[120:123]
	v_mfma_f32_16x16x32_bf16 v[108:111], v[128:131], v[168:171], v[108:111]
	v_mfma_f32_16x16x32_bf16 v[104:107], v[152:155], v[168:171], v[104:107]
	v_mfma_f32_16x16x32_bf16 v[92:95], v[128:131], v[180:183], v[92:95]
	v_mfma_f32_16x16x32_bf16 v[88:91], v[152:155], v[180:183], v[88:91]
	v_mfma_f32_16x16x32_bf16 v[76:79], v[128:131], v[188:191], v[76:79]
	v_mfma_f32_16x16x32_bf16 v[72:75], v[152:155], v[188:191], v[72:75]
	v_mfma_f32_16x16x32_bf16 v[124:127], v[148:151], v[164:167], v[124:127]
	v_mfma_f32_16x16x32_bf16 v[120:123], v[156:159], v[164:167], v[120:123]
	v_mfma_f32_16x16x32_bf16 v[108:111], v[148:151], v[176:179], v[108:111]
	v_mfma_f32_16x16x32_bf16 v[104:107], v[156:159], v[176:179], v[104:107]
	v_mfma_f32_16x16x32_bf16 v[92:95], v[148:151], v[184:187], v[92:95]
	v_mfma_f32_16x16x32_bf16 v[88:91], v[156:159], v[184:187], v[88:91]
	v_mfma_f32_16x16x32_bf16 v[76:79], v[148:151], v[192:195], v[76:79]
	v_mfma_f32_16x16x32_bf16 v[72:75], v[156:159], v[192:195], v[72:75]
	s_setprio 0
	s_barrier
	s_add_i32 s26, 0, 0x1c000
	s_add_i32 s27, s28, s97
	v_add_u32_e32 v208, s26, v173
	v_lshl_add_u64 v[212:213], v[212:213], 0, s[22:23]
	s_mov_b32 m0, s27
	ds_read_b128 v[196:199], v208
	ds_read_b128 v[200:203], v208 offset:1024
	ds_read_b128 v[204:207], v208 offset:2048
	ds_read_b128 v[208:211], v208 offset:3072
	global_load_lds_dwordx4 v[212:213], off
	v_lshl_add_u64 v[212:213], v[214:215], 0, s[22:23]
	s_add_i32 m0, s27, 0x2000
	s_nop 0
	global_load_lds_dwordx4 v[212:213], off
	s_barrier
	s_waitcnt lgkmcnt(0)
	s_setprio 1
	s_waitcnt lgkmcnt(0)
	v_mfma_f32_16x16x32_bf16 v[116:119], v[196:199], v[160:163], v[116:119]
	v_mfma_f32_16x16x32_bf16 v[112:115], v[204:207], v[160:163], v[112:115]
	v_mfma_f32_16x16x32_bf16 v[100:103], v[196:199], v[168:171], v[100:103]
	v_mfma_f32_16x16x32_bf16 v[96:99], v[204:207], v[168:171], v[96:99]
	v_mfma_f32_16x16x32_bf16 v[84:87], v[196:199], v[180:183], v[84:87]
	v_mfma_f32_16x16x32_bf16 v[80:83], v[204:207], v[180:183], v[80:83]
	v_mfma_f32_16x16x32_bf16 v[68:71], v[196:199], v[188:191], v[68:71]
	v_mfma_f32_16x16x32_bf16 v[64:67], v[204:207], v[188:191], v[64:67]
	v_mfma_f32_16x16x32_bf16 v[116:119], v[200:203], v[164:167], v[116:119]
	v_mfma_f32_16x16x32_bf16 v[112:115], v[208:211], v[164:167], v[112:115]
	v_mfma_f32_16x16x32_bf16 v[100:103], v[200:203], v[176:179], v[100:103]
	v_mfma_f32_16x16x32_bf16 v[96:99], v[208:211], v[176:179], v[96:99]
	v_mfma_f32_16x16x32_bf16 v[84:87], v[200:203], v[184:187], v[84:87]
	v_mfma_f32_16x16x32_bf16 v[80:83], v[208:211], v[184:187], v[80:83]
	v_mfma_f32_16x16x32_bf16 v[68:71], v[200:203], v[192:195], v[68:71]
	v_mfma_f32_16x16x32_bf16 v[64:67], v[208:211], v[192:195], v[64:67]
	s_setprio 0
	s_mov_b32 m0, s74
	v_lshl_add_u64 v[212:213], v[216:217], 0, s[22:23]
	s_barrier
; #define PG8_STAGE(bufoff, gbase, voff) do { _Pragma("unroll") for (int _i = 0; _i < 2; ++_i) \
;     __builtin_amdgcn_global_load_lds((const unsigned*)((const char*)(gbase) + (voff)[_i]), (LAS unsigned*)(lds + (bufoff) + ldsw + _i * 8192), 16, 0, 0); } while (0)
; #define PG8_LDA(dst, b, h) do { _Pragma("unroll") for (int m = 0; m < 4; ++m) _Pragma("unroll") for (int k = 0; k < 2; ++k) dst[m][k] = *(const LAS bf16x8*)(lds + PG8_SA(b, h) + aoff + m * 2048 + k * 1024); } while (0)
; #define PG8_MMA(ai, bj, At, Bt) do { __builtin_amdgcn_s_setprio(1); _Pragma("unroll") for (int m = 0; m < 4; ++m) _Pragma("unroll") for (int n = 0; n < 2; ++n) _Pragma("unroll") for (int k = 0; k < 2; ++k) \
;     acc[ai][bj][m][n] = __builtin_amdgcn_mfma_f32_16x16x32_bf16(Bt[n][k], At[m][k], acc[ai][bj][m][n], 0, 0, 0); __builtin_amdgcn_s_setprio(0); } while (0)
; #define PG8_WAIT_V(n) asm volatile("s_waitcnt vmcnt(" #n ")" ::: "memory")
; #define PG8_WAIT_L(n) asm volatile("s_waitcnt lgkmcnt(" #n ")" ::: "memory")
; #define PG8_BAR __builtin_amdgcn_s_barrier()
; #define PG8_SCHED __builtin_amdgcn_sched_barrier(0)
; template <class Epi>
; __device__ __forceinline__ void gemm_phase(LAS unsigned char* lds, const Gemm g, const Epi& E) {
;     ...
;       PG8_LDA(At, 1, 1); PG8_STAGE(PG8_SA(1, 0), a3, voffA);
;       PG8_BAR; PG8_WAIT_L(0); PG8_MMA(1, 0, At, B0); PG8_BAR; PG8_SCHED;
;       PG8_STAGE(PG8_SB(1, 1), b3 + hstepB, voffB);
;       PG8_WAIT_V(6); PG8_BAR; PG8_MMA(1, 1, At, B1); PG8_BAR;
;     }
;     {
; #pragma unroll
;       for (int ai = 0; ai < 2; ++ai)
; #pragma unroll
;         for (int m = 0; m < 4; ++m)
; #pragma unroll
;           for (int bj = 0; bj < 2; ++bj)
;           { E.st2(cur.w, cur.pm * BM + ai * HALF + wr * 64 + m * 16 + fr, cur.pn * BM + bj * HALF + wc * 32 + 8 * fq, acc[ai][bj][m][0], acc[ai][bj][m][1]); if (bj == 1 && (m & 1)) asm volatile("" ::: "memory"); }
	ds_read_b128 v[160:163], v175 offset:49152
	ds_read_b128 v[164:167], v175 offset:50176
	ds_read_b128 v[168:171], v175 offset:51200
	ds_read_b128 v[176:179], v175 offset:52224
	ds_read_b128 v[180:183], v175 offset:53248
	ds_read_b128 v[184:187], v175 offset:54272
	ds_read_b128 v[188:191], v175 offset:55296
	ds_read_b128 v[192:195], v175 offset:56320
	global_load_lds_dwordx4 v[212:213], off
	v_lshl_add_u64 v[212:213], v[218:219], 0, s[22:23]
	s_mov_b32 m0, s78
	s_nop 0
	global_load_lds_dwordx4 v[212:213], off
	s_barrier
	s_waitcnt lgkmcnt(0)
	s_setprio 1
	s_waitcnt lgkmcnt(0)
	v_mfma_f32_16x16x32_bf16 v[60:63], v[128:131], v[160:163], v[60:63]
	v_mfma_f32_16x16x32_bf16 v[56:59], v[152:155], v[160:163], v[56:59]
	v_mfma_f32_16x16x32_bf16 v[44:47], v[128:131], v[168:171], v[44:47]
	v_mfma_f32_16x16x32_bf16 v[40:43], v[152:155], v[168:171], v[40:43]
	v_mfma_f32_16x16x32_bf16 v[28:31], v[128:131], v[180:183], v[28:31]
	v_mfma_f32_16x16x32_bf16 v[24:27], v[152:155], v[180:183], v[24:27]
	v_mfma_f32_16x16x32_bf16 v[12:15], v[128:131], v[188:191], v[12:15]
	v_mfma_f32_16x16x32_bf16 v[8:11], v[152:155], v[188:191], v[8:11]
	v_mfma_f32_16x16x32_bf16 v[60:63], v[148:151], v[164:167], v[60:63]
	v_mfma_f32_16x16x32_bf16 v[56:59], v[156:159], v[164:167], v[56:59]
	v_mfma_f32_16x16x32_bf16 v[44:47], v[148:151], v[176:179], v[44:47]
	v_mfma_f32_16x16x32_bf16 v[40:43], v[156:159], v[176:179], v[40:43]
	v_mfma_f32_16x16x32_bf16 v[28:31], v[148:151], v[184:187], v[28:31]
	v_mfma_f32_16x16x32_bf16 v[24:27], v[156:159], v[184:187], v[24:27]
	v_mfma_f32_16x16x32_bf16 v[12:15], v[148:151], v[192:195], v[12:15]
	v_mfma_f32_16x16x32_bf16 v[8:11], v[156:159], v[192:195], v[8:11]
	s_setprio 0
	s_barrier
	s_add_i32 s26, s26, s97
	v_lshl_add_u64 v[128:129], v[220:221], 0, s[22:23]
	s_mov_b32 m0, s26
	s_nop 0
	global_load_lds_dwordx4 v[128:129], off
	v_lshl_add_u64 v[128:129], v[222:223], 0, s[22:23]
	s_add_i32 m0, s26, 0x2000
	s_nop 0
	global_load_lds_dwordx4 v[128:129], off
	s_waitcnt vmcnt(6)
	s_barrier
	s_setprio 1
	v_mfma_f32_16x16x32_bf16 v[52:55], v[196:199], v[160:163], v[52:55]
	v_mfma_f32_16x16x32_bf16 v[48:51], v[204:207], v[160:163], v[48:51]
	v_mfma_f32_16x16x32_bf16 v[36:39], v[196:199], v[168:171], v[36:39]
	v_mfma_f32_16x16x32_bf16 v[32:35], v[204:207], v[168:171], v[32:35]
	v_mfma_f32_16x16x32_bf16 v[20:23], v[196:199], v[180:183], v[20:23]
	v_mfma_f32_16x16x32_bf16 v[16:19], v[204:207], v[180:183], v[16:19]
	v_mfma_f32_16x16x32_bf16 v[4:7], v[196:199], v[188:191], v[4:7]
	v_mfma_f32_16x16x32_bf16 v[0:3], v[204:207], v[188:191], v[0:3]
	v_mfma_f32_16x16x32_bf16 v[52:55], v[200:203], v[164:167], v[52:55]
	v_mfma_f32_16x16x32_bf16 v[48:51], v[208:211], v[164:167], v[48:51]
	v_mfma_f32_16x16x32_bf16 v[36:39], v[200:203], v[176:179], v[36:39]
	v_mfma_f32_16x16x32_bf16 v[32:35], v[208:211], v[176:179], v[32:35]
	v_mfma_f32_16x16x32_bf16 v[20:23], v[200:203], v[184:187], v[20:23]
	v_mfma_f32_16x16x32_bf16 v[16:19], v[208:211], v[184:187], v[16:19]
	v_mfma_f32_16x16x32_bf16 v[4:7], v[200:203], v[192:195], v[4:7]
	v_mfma_f32_16x16x32_bf16 v[0:3], v[208:211], v[192:195], v[0:3]
	s_setprio 0
	s_add_u32 s2, s2, 0x100
	s_addc_u32 s3, s3, 0
	s_add_u32 s38, s38, 0x100
	s_addc_u32 s39, s39, 0
	s_cmp_ge_u32 s76, s72
	s_mov_b32 s26, s76
	s_barrier
	s_cbranch_scc0 .LBB0_579
	s_lshl_b32 s28, s53, 8
	v_lshl_add_u32 v150, s75, 8, v172
	s_cmp_eq_u32 s12, 0
	v_ashrrev_i32_e32 v151, 31, v150
	v_mad_i64_i32 v[164:165], s[2:3], v150, s54, 0
	v_mad_i64_i32 v[154:155], s[2:3], v150, s33, 0
	s_cselect_b32 s29, s40, s41
	v_lshlrev_b64 v[162:163], 10, v[150:151]
	v_cmp_gt_i32_e64 s[38:39], s92, v150
	v_lshlrev_b64 v[152:153], 12, v[150:151]
	v_or_b32_e32 v148, s28, v174
	s_cmp_eq_u32 s29, 3
	s_cbranch_scc1 .Lepi3
	s_cmp_eq_u32 s29, 4
	s_cbranch_scc1 .Lepi4
	s_cmp_eq_u32 s29, 6
	s_cbranch_scc1 .Lepi6
	s_cmp_eq_u32 s29, 0
	s_cbranch_scc1 .Lepi0
	s_cmp_eq_u32 s29, 1
	s_cbranch_scc1 .Lepi1
	s_cmp_eq_u32 s29, 2
	s_cbranch_scc1 .Lepi2
	s_cmp_lt_i32 s29, 4
	s_mov_b64 s[2:3], -1
	s_cbranch_scc1 .LBB0_593
	s_cmp_lt_i32 s29, 6
	s_cbranch_scc1 .LBB0_587
	s_cmp_gt_i32 s29, 6
	s_cbranch_scc0 .LBB0_584
	v_lshl_add_u64 v[128:129], s[58:59], 0, v[152:153]
	v_ashrrev_i32_e32 v149, 31, v148
	v_lshl_add_u64 v[160:161], v[148:149], 2, v[128:129]
	global_load_dwordx4 v[128:131], v[160:161], off nt
	global_load_dwordx4 v[156:159], v[160:161], off offset:16 nt
	s_mov_b64 s[2:3], 0
	s_waitcnt vmcnt(0)
	v_pk_add_f32 v[130:131], v[126:127], v[130:131]
	v_pk_add_f32 v[128:129], v[124:125], v[128:129]
	v_pk_add_f32 v[158:159], v[122:123], v[158:159]
	v_pk_add_f32 v[156:157], v[120:121], v[156:157]
	global_store_dwordx4 v[160:161], v[128:131], off nt
	global_store_dwordx4 v[160:161], v[156:159], off offset:16 nt

.Lepi0:
	s_cmpk_lt_u32 s28, 0x400
	s_cbranch_scc1 .Lepi0_b1
	s_cmpk_lt_u32 s28, 0xc00
	s_cbranch_scc1 .Lepi0_b2
	s_cmpk_lt_u32 s28, 0x1800
	s_cbranch_scc1 .Lepi0_g3
	v_readlane_b32 s26, v255, 27
	v_readlane_b32 s27, v255, 28
	v_lshlrev_b32_e32 v176, 9, v150
	v_lshl_add_u32 v176, v148, 1, v176
	v_add_u32_e32 v176, 0xffffd000, v176
	s_mov_b32 s2, 0x2000
	s_mov_b32 s3, 0x10000
	s_branch .Lepi0_go
.Lepi0_b1:
	s_mov_b64 s[26:27], s[64:65]
	v_lshlrev_b32_e32 v176, 11, v150
	v_lshl_add_u32 v176, v148, 1, v176
	s_mov_b32 s2, 0x8000
	s_mov_b32 s3, 0x40000
	s_branch .Lepi0_go
.Lepi0_b2:
	s_mov_b64 s[26:27], s[66:67]
	v_lshlrev_b32_e32 v176, 12, v150
	v_lshl_add_u32 v176, v148, 1, v176
	v_add_u32_e32 v176, 0xfffff800, v176
	s_mov_b32 s2, 0x10000
	s_mov_b32 s3, 0x80000
	s_branch .Lepi0_go
.Lepi0_g3:
	s_lshl_b32 s2, s75, 8
	s_cmp_ge_u32 s2, s92
	s_cbranch_scc1 .Lepi0_done
	s_mov_b64 s[26:27], s[68:69]
	v_mul_u32_u24_e32 v176, 0x1800, v150
	v_lshl_add_u32 v176, v148, 1, v176
	v_add_u32_e32 v176, 0xffffe800, v176
	s_mov_b32 s2, 0x18000
	s_mov_b32 s3, 0xc0000
	s_branch .Lepi0_go
.Lepi1:
	s_mov_b64 s[26:27], s[64:65]
	v_mul_u32_u24_e32 v176, 0xc00, v150
	v_lshl_add_u32 v176, v148, 1, v176
	s_mov_b32 s2, 0xc000
	s_mov_b32 s3, 0x60000
	s_branch .Lepi0_go
.Lepi2:
	s_cmpk_lt_u32 s28, 0x400
	s_cbranch_scc1 .Lepi0_b1
	s_mov_b64 s[26:27], s[66:67]
	v_lshlrev_b32_e32 v176, 11, v150
	v_lshl_add_u32 v176, v148, 1, v176
	v_add_u32_e32 v176, 0xfffff800, v176
	s_mov_b32 s2, 0x8000
	s_mov_b32 s3, 0x40000
.Lepi0_go:
	v_add_u32_e32 v177, s2, v176
	v_add_u32_e32 v178, s2, v177
	v_add_u32_e32 v179, s2, v178
	v_add_u32_e32 v180, s3, v176
	v_add_u32_e32 v181, s2, v180
	v_add_u32_e32 v182, s2, v181
	v_add_u32_e32 v183, s2, v182
	v_cvt_pk_bf16_f32 v184, v124, v125
	v_cvt_pk_bf16_f32 v185, v126, v127
	v_cvt_pk_bf16_f32 v186, v120, v121
	v_cvt_pk_bf16_f32 v187, v122, v123
	global_store_dwordx4 v176, v[184:187], s[26:27]
	v_cvt_pk_bf16_f32 v188, v116, v117
	v_cvt_pk_bf16_f32 v189, v118, v119
	v_cvt_pk_bf16_f32 v190, v112, v113
	v_cvt_pk_bf16_f32 v191, v114, v115
	global_store_dwordx4 v176, v[188:191], s[26:27] offset:256
	v_cvt_pk_bf16_f32 v184, v108, v109
	v_cvt_pk_bf16_f32 v185, v110, v111
	v_cvt_pk_bf16_f32 v186, v104, v105
	v_cvt_pk_bf16_f32 v187, v106, v107
	global_store_dwordx4 v177, v[184:187], s[26:27]
	v_cvt_pk_bf16_f32 v188, v100, v101
	v_cvt_pk_bf16_f32 v189, v102, v103
	v_cvt_pk_bf16_f32 v190, v96, v97
	v_cvt_pk_bf16_f32 v191, v98, v99
	global_store_dwordx4 v177, v[188:191], s[26:27] offset:256
	v_cvt_pk_bf16_f32 v184, v92, v93
	v_cvt_pk_bf16_f32 v185, v94, v95
	v_cvt_pk_bf16_f32 v186, v88, v89
	v_cvt_pk_bf16_f32 v187, v90, v91
	global_store_dwordx4 v178, v[184:187], s[26:27]
	v_cvt_pk_bf16_f32 v188, v84, v85
	v_cvt_pk_bf16_f32 v189, v86, v87
	v_cvt_pk_bf16_f32 v190, v80, v81
	v_cvt_pk_bf16_f32 v191, v82, v83
	global_store_dwordx4 v178, v[188:191], s[26:27] offset:256
	v_cvt_pk_bf16_f32 v184, v76, v77
	v_cvt_pk_bf16_f32 v185, v78, v79
	v_cvt_pk_bf16_f32 v186, v72, v73
	v_cvt_pk_bf16_f32 v187, v74, v75
	global_store_dwordx4 v179, v[184:187], s[26:27]
	v_cvt_pk_bf16_f32 v188, v68, v69
	v_cvt_pk_bf16_f32 v189, v70, v71
	v_cvt_pk_bf16_f32 v190, v64, v65
	v_cvt_pk_bf16_f32 v191, v66, v67
	global_store_dwordx4 v179, v[188:191], s[26:27] offset:256
	v_cvt_pk_bf16_f32 v184, v60, v61
	v_cvt_pk_bf16_f32 v185, v62, v63
	v_cvt_pk_bf16_f32 v186, v56, v57
	v_cvt_pk_bf16_f32 v187, v58, v59
	global_store_dwordx4 v180, v[184:187], s[26:27]
	v_cvt_pk_bf16_f32 v188, v52, v53
	v_cvt_pk_bf16_f32 v189, v54, v55
	v_cvt_pk_bf16_f32 v190, v48, v49
	v_cvt_pk_bf16_f32 v191, v50, v51
	global_store_dwordx4 v180, v[188:191], s[26:27] offset:256
	v_cvt_pk_bf16_f32 v184, v44, v45
	v_cvt_pk_bf16_f32 v185, v46, v47
	v_cvt_pk_bf16_f32 v186, v40, v41
	v_cvt_pk_bf16_f32 v187, v42, v43
	global_store_dwordx4 v181, v[184:187], s[26:27]
	v_cvt_pk_bf16_f32 v188, v36, v37
	v_cvt_pk_bf16_f32 v189, v38, v39
	v_cvt_pk_bf16_f32 v190, v32, v33
	v_cvt_pk_bf16_f32 v191, v34, v35
	global_store_dwordx4 v181, v[188:191], s[26:27] offset:256
	v_cvt_pk_bf16_f32 v184, v28, v29
	v_cvt_pk_bf16_f32 v185, v30, v31
	v_cvt_pk_bf16_f32 v186, v24, v25
	v_cvt_pk_bf16_f32 v187, v26, v27
	global_store_dwordx4 v182, v[184:187], s[26:27]
	v_cvt_pk_bf16_f32 v188, v20, v21
	v_cvt_pk_bf16_f32 v189, v22, v23
	v_cvt_pk_bf16_f32 v190, v16, v17
	v_cvt_pk_bf16_f32 v191, v18, v19
	global_store_dwordx4 v182, v[188:191], s[26:27] offset:256
	v_cvt_pk_bf16_f32 v184, v12, v13
	v_cvt_pk_bf16_f32 v185, v14, v15
	v_cvt_pk_bf16_f32 v186, v8, v9
	v_cvt_pk_bf16_f32 v187, v10, v11
	global_store_dwordx4 v183, v[184:187], s[26:27]
	v_cvt_pk_bf16_f32 v188, v4, v5
	v_cvt_pk_bf16_f32 v189, v6, v7
	v_cvt_pk_bf16_f32 v190, v0, v1
	v_cvt_pk_bf16_f32 v191, v2, v3
	global_store_dwordx4 v183, v[188:191], s[26:27] offset:256
.Lepi0_done:
	s_branch .LBB0_567
